# combined: early acquire + exact last-iteration wait counts + short K back edge + no-tile items skip their token wait
# speedup vs baseline: 1.0040x; 1.0040x over previous
.Lc0s_final:
	s_add_i32 s62, s58, 0xfff80080
	s_and_b64 s[10:11], s[10:11], exec
	s_cselect_b32 s78, s54, s62
	s_cselect_b32 s62, s55, s60
	s_add_i32 s10, 0, 0x10000
	v_add_u32_e32 v0, s10, v157
	v_add_u32_e32 v147, s10, v158
	s_add_i32 s10, 0, 0x14000
	ds_read_b128 v[164:167], v0
	ds_read_b128 v[168:171], v0 offset:2048
	ds_read_b128 v[172:175], v147
	ds_read_b128 v[176:179], v147 offset:2048
	v_add_u32_e32 v0, s10, v157
	v_add_u32_e32 v147, s10, v158
	ds_read_b128 v[180:183], v0
	ds_read_b128 v[184:187], v0 offset:2048
	ds_read_b128 v[188:191], v147
	ds_read_b128 v[192:195], v147 offset:2048
	s_or_b32 s64, s78, 0x80
	s_or_b32 s65, s62, 0x80
	s_mov_b32 m0, s41
	ds_read_b128 v[196:199], v161
	ds_read_b128 v[204:207], v161 offset:2048
	ds_read_b128 v[208:211], v162
	ds_read_b128 v[212:215], v162 offset:2048
	ds_read_b128 v[216:219], v161 offset:4096
	ds_read_b128 v[220:223], v161 offset:6144
	ds_read_b128 v[224:227], v162 offset:4096
	ds_read_b128 v[228:231], v162 offset:6144
	buffer_load_dwordx4 v153, s[48:51], s58 offen lds
	s_mov_b32 m0, s42
	s_nop 0
	buffer_load_dwordx4 v155, s[48:51], s58 offen lds
	s_waitcnt vmcnt(16)
	s_waitcnt lgkmcnt(0)
	s_barrier
	s_waitcnt lgkmcnt(0)
	v_readlane_b32 s32, v255, 9
	s_cmp_lg_u32 s32, 0
	s_cbranch_scc1 .Lei_p1_c0s
	s_cmp_lt_i32 s63, 1
	s_cbranch_scc1 .Lei_p1_c0s
	v_readlane_b32 s32, v255, 12
	s_nop 1
	v_mov_b32_e32 v232, s32
	v_readlane_b32 s32, v255, 13
	s_nop 1
	v_mov_b32_e32 v233, s32
	s_mul_i32 s32, s63, 0x220
	s_sub_u32 s32, s32, 32
	v_mov_b32_e32 v234, s32
	v_mov_b32_e32 v235, 0
	v_lshl_add_u64 v[232:233], v[232:233], 0, v[234:235]
	v_readlane_b32 s32, v255, 17
	s_nop 1
	v_mov_b32_e32 v235, s32
	global_load_dword v234, v[232:233], off sc1
	ds_read_b32 v235, v235
.Lei_p1_c0s:
	v_mfma_f32_16x16x32_f16 v[118:121], v[164:167], v[196:199], v[118:121]
	v_mfma_f32_16x16x32_f16 v[110:113], v[168:171], v[196:199], v[110:113]
	v_mfma_f32_16x16x32_f16 v[102:105], v[164:167], v[204:207], v[102:105]
	v_mfma_f32_16x16x32_f16 v[94:97], v[168:171], v[204:207], v[94:97]
	v_mfma_f32_16x16x32_f16 v[86:89], v[164:167], v[216:219], v[86:89]
	v_mfma_f32_16x16x32_f16 v[78:81], v[168:171], v[216:219], v[78:81]
	v_mfma_f32_16x16x32_f16 v[66:69], v[164:167], v[220:223], v[66:69]
	v_mfma_f32_16x16x32_f16 v[58:61], v[168:171], v[220:223], v[58:61]
	v_mfma_f32_16x16x32_f16 v[118:121], v[172:175], v[208:211], v[118:121]
	v_mfma_f32_16x16x32_f16 v[110:113], v[176:179], v[208:211], v[110:113]
	v_mfma_f32_16x16x32_f16 v[102:105], v[172:175], v[212:215], v[102:105]
	v_mfma_f32_16x16x32_f16 v[94:97], v[176:179], v[212:215], v[94:97]
	v_mfma_f32_16x16x32_f16 v[86:89], v[172:175], v[224:227], v[86:89]
	v_mfma_f32_16x16x32_f16 v[78:81], v[176:179], v[224:227], v[78:81]
	v_mfma_f32_16x16x32_f16 v[66:69], v[172:175], v[228:231], v[66:69]
	v_mfma_f32_16x16x32_f16 v[58:61], v[176:179], v[228:231], v[58:61]
	v_mfma_f32_16x16x32_f16 v[126:129], v[180:183], v[196:199], v[126:129]
	v_mfma_f32_16x16x32_f16 v[122:125], v[184:187], v[196:199], v[122:125]
	v_mfma_f32_16x16x32_f16 v[114:117], v[180:183], v[204:207], v[114:117]
	v_mfma_f32_16x16x32_f16 v[106:109], v[184:187], v[204:207], v[106:109]
	v_mfma_f32_16x16x32_f16 v[98:101], v[180:183], v[216:219], v[98:101]
	v_mfma_f32_16x16x32_f16 v[90:93], v[184:187], v[216:219], v[90:93]
	v_mfma_f32_16x16x32_f16 v[82:85], v[180:183], v[220:223], v[82:85]
	v_mfma_f32_16x16x32_f16 v[74:77], v[184:187], v[220:223], v[74:77]
	v_mfma_f32_16x16x32_f16 v[126:129], v[188:191], v[208:211], v[126:129]
	v_mfma_f32_16x16x32_f16 v[122:125], v[192:195], v[208:211], v[122:125]
	v_mfma_f32_16x16x32_f16 v[114:117], v[188:191], v[212:215], v[114:117]
	v_mfma_f32_16x16x32_f16 v[106:109], v[192:195], v[212:215], v[106:109]
	v_mfma_f32_16x16x32_f16 v[98:101], v[188:191], v[224:227], v[98:101]
	v_mfma_f32_16x16x32_f16 v[90:93], v[192:195], v[224:227], v[90:93]
	v_mfma_f32_16x16x32_f16 v[82:85], v[188:191], v[228:231], v[82:85]
	v_mfma_f32_16x16x32_f16 v[74:77], v[192:195], v[228:231], v[74:77]
	s_barrier
	s_mov_b32 s10, s50
	s_mov_b32 s11, s51
	ds_read_b128 v[196:199], v161 offset:16384
	ds_read_b128 v[204:207], v161 offset:18432
	ds_read_b128 v[208:211], v162 offset:16384
	ds_read_b128 v[212:215], v162 offset:18432
	ds_read_b128 v[216:219], v161 offset:20480
	ds_read_b128 v[220:223], v161 offset:22528
	ds_read_b128 v[224:227], v162 offset:20480
	ds_read_b128 v[228:231], v162 offset:22528
	s_add_i32 s81, s62, 0x80000
	s_waitcnt vmcnt(10)
	s_waitcnt lgkmcnt(0)
	s_barrier
	s_waitcnt lgkmcnt(0)
	v_mfma_f32_16x16x32_f16 v[54:57], v[164:167], v[196:199], v[54:57]
	v_mfma_f32_16x16x32_f16 v[46:49], v[168:171], v[196:199], v[46:49]
	v_mfma_f32_16x16x32_f16 v[38:41], v[164:167], v[204:207], v[38:41]
	v_mfma_f32_16x16x32_f16 v[30:33], v[168:171], v[204:207], v[30:33]
	v_mfma_f32_16x16x32_f16 v[22:25], v[164:167], v[216:219], v[22:25]
	v_mfma_f32_16x16x32_f16 v[14:17], v[168:171], v[216:219], v[14:17]
	v_mfma_f32_16x16x32_f16 v[6:9], v[164:167], v[220:223], v[6:9]
	v_mfma_f32_16x16x32_f16 v[2:5], v[168:171], v[220:223], v[2:5]
	v_mfma_f32_16x16x32_f16 v[54:57], v[172:175], v[208:211], v[54:57]
	v_mfma_f32_16x16x32_f16 v[46:49], v[176:179], v[208:211], v[46:49]
	v_mfma_f32_16x16x32_f16 v[38:41], v[172:175], v[212:215], v[38:41]
	v_mfma_f32_16x16x32_f16 v[30:33], v[176:179], v[212:215], v[30:33]
	v_mfma_f32_16x16x32_f16 v[22:25], v[172:175], v[224:227], v[22:25]
	v_mfma_f32_16x16x32_f16 v[14:17], v[176:179], v[224:227], v[14:17]
	v_mfma_f32_16x16x32_f16 v[6:9], v[172:175], v[228:231], v[6:9]
	v_mfma_f32_16x16x32_f16 v[2:5], v[176:179], v[228:231], v[2:5]
	v_mfma_f32_16x16x32_f16 v[70:73], v[180:183], v[196:199], v[70:73]
	v_mfma_f32_16x16x32_f16 v[62:65], v[184:187], v[196:199], v[62:65]
	v_mfma_f32_16x16x32_f16 v[50:53], v[180:183], v[204:207], v[50:53]
	v_mfma_f32_16x16x32_f16 v[42:45], v[184:187], v[204:207], v[42:45]
	v_mfma_f32_16x16x32_f16 v[34:37], v[180:183], v[216:219], v[34:37]
	v_mfma_f32_16x16x32_f16 v[26:29], v[184:187], v[216:219], v[26:29]
	v_mfma_f32_16x16x32_f16 v[18:21], v[180:183], v[220:223], v[18:21]
	v_mfma_f32_16x16x32_f16 v[10:13], v[184:187], v[220:223], v[10:13]
	v_mfma_f32_16x16x32_f16 v[70:73], v[188:191], v[208:211], v[70:73]
	v_mfma_f32_16x16x32_f16 v[62:65], v[192:195], v[208:211], v[62:65]
	v_mfma_f32_16x16x32_f16 v[50:53], v[188:191], v[212:215], v[50:53]
	v_mfma_f32_16x16x32_f16 v[42:45], v[192:195], v[212:215], v[42:45]
	v_mfma_f32_16x16x32_f16 v[34:37], v[188:191], v[224:227], v[34:37]
	v_mfma_f32_16x16x32_f16 v[26:29], v[192:195], v[224:227], v[26:29]
	v_mfma_f32_16x16x32_f16 v[18:21], v[188:191], v[228:231], v[18:21]
	v_mfma_f32_16x16x32_f16 v[10:13], v[192:195], v[228:231], v[10:13]
	s_barrier
	s_add_i32 s81, 0, 0x18000
	v_add_u32_e32 v0, s81, v157
	v_add_u32_e32 v147, s81, v158
	s_add_i32 s81, 0, 0x1c000
	ds_read_b128 v[164:167], v0
	ds_read_b128 v[168:171], v0 offset:2048
	ds_read_b128 v[172:175], v147
	ds_read_b128 v[176:179], v147 offset:2048
	v_add_u32_e32 v0, s81, v157
	v_add_u32_e32 v147, s81, v158
	ds_read_b128 v[180:183], v0
	ds_read_b128 v[184:187], v0 offset:2048
	ds_read_b128 v[188:191], v147
	ds_read_b128 v[192:195], v147 offset:2048
	s_add_i32 s78, s78, 0x80000
	ds_read_b128 v[196:199], v161 offset:32768
	ds_read_b128 v[204:207], v161 offset:34816
	ds_read_b128 v[208:211], v162 offset:32768
	ds_read_b128 v[212:215], v162 offset:34816
	ds_read_b128 v[216:219], v161 offset:36864
	ds_read_b128 v[220:223], v161 offset:38912
	ds_read_b128 v[224:227], v162 offset:36864
	ds_read_b128 v[228:231], v162 offset:38912
	s_waitcnt vmcnt(0)
	s_waitcnt lgkmcnt(0)
	s_barrier
	s_waitcnt lgkmcnt(0)
	v_mfma_f32_16x16x32_f16 v[118:121], v[164:167], v[196:199], v[118:121]
	v_mfma_f32_16x16x32_f16 v[110:113], v[168:171], v[196:199], v[110:113]
	v_mfma_f32_16x16x32_f16 v[102:105], v[164:167], v[204:207], v[102:105]
	v_mfma_f32_16x16x32_f16 v[94:97], v[168:171], v[204:207], v[94:97]
	v_mfma_f32_16x16x32_f16 v[86:89], v[164:167], v[216:219], v[86:89]
	v_mfma_f32_16x16x32_f16 v[78:81], v[168:171], v[216:219], v[78:81]
	v_mfma_f32_16x16x32_f16 v[66:69], v[164:167], v[220:223], v[66:69]
	v_mfma_f32_16x16x32_f16 v[58:61], v[168:171], v[220:223], v[58:61]
	v_mfma_f32_16x16x32_f16 v[118:121], v[172:175], v[208:211], v[118:121]
	v_mfma_f32_16x16x32_f16 v[110:113], v[176:179], v[208:211], v[110:113]
	v_mfma_f32_16x16x32_f16 v[102:105], v[172:175], v[212:215], v[102:105]
	v_mfma_f32_16x16x32_f16 v[94:97], v[176:179], v[212:215], v[94:97]
	v_mfma_f32_16x16x32_f16 v[86:89], v[172:175], v[224:227], v[86:89]
	v_mfma_f32_16x16x32_f16 v[78:81], v[176:179], v[224:227], v[78:81]
	v_mfma_f32_16x16x32_f16 v[66:69], v[172:175], v[228:231], v[66:69]
	v_mfma_f32_16x16x32_f16 v[58:61], v[176:179], v[228:231], v[58:61]
	v_mfma_f32_16x16x32_f16 v[126:129], v[180:183], v[196:199], v[126:129]
	v_mfma_f32_16x16x32_f16 v[122:125], v[184:187], v[196:199], v[122:125]
	v_mfma_f32_16x16x32_f16 v[114:117], v[180:183], v[204:207], v[114:117]
	v_mfma_f32_16x16x32_f16 v[106:109], v[184:187], v[204:207], v[106:109]
	v_mfma_f32_16x16x32_f16 v[98:101], v[180:183], v[216:219], v[98:101]
	v_mfma_f32_16x16x32_f16 v[90:93], v[184:187], v[216:219], v[90:93]
	v_mfma_f32_16x16x32_f16 v[82:85], v[180:183], v[220:223], v[82:85]
	v_mfma_f32_16x16x32_f16 v[74:77], v[184:187], v[220:223], v[74:77]
	v_mfma_f32_16x16x32_f16 v[126:129], v[188:191], v[208:211], v[126:129]
	v_mfma_f32_16x16x32_f16 v[122:125], v[192:195], v[208:211], v[122:125]
	v_mfma_f32_16x16x32_f16 v[114:117], v[188:191], v[212:215], v[114:117]
	v_mfma_f32_16x16x32_f16 v[106:109], v[192:195], v[212:215], v[106:109]
	v_mfma_f32_16x16x32_f16 v[98:101], v[188:191], v[224:227], v[98:101]
	v_mfma_f32_16x16x32_f16 v[90:93], v[192:195], v[224:227], v[90:93]
	v_mfma_f32_16x16x32_f16 v[82:85], v[188:191], v[228:231], v[82:85]
	v_mfma_f32_16x16x32_f16 v[74:77], v[192:195], v[228:231], v[74:77]
	s_barrier
	ds_read_b128 v[196:199], v161 offset:49152
	ds_read_b128 v[204:207], v161 offset:51200
	ds_read_b128 v[208:211], v162 offset:49152
	ds_read_b128 v[212:215], v162 offset:51200
	ds_read_b128 v[216:219], v161 offset:53248
	ds_read_b128 v[220:223], v161 offset:55296
	ds_read_b128 v[224:227], v162 offset:53248
	ds_read_b128 v[228:231], v162 offset:55296
	s_add_i32 s62, s62, 0x80080
	s_waitcnt vmcnt(0)
	s_waitcnt lgkmcnt(0)
	s_barrier
	s_waitcnt lgkmcnt(0)
	v_readlane_b32 s32, v255, 9
	s_cmp_lg_u32 s32, 0
	s_cbranch_scc1 .Lei_p2_c0s
	s_cmp_lt_i32 s63, 1
	s_cbranch_scc1 .Lei_p2_c0s
	v_sub_u32_e32 v234, v234, v235
	s_nop 0
	v_readfirstlane_b32 s32, v234
	s_cmp_lt_i32 s32, 0
	s_cbranch_scc1 .Lei_p2_c0s
	buffer_inv sc1
	v_writelane_b32 v255, 1, 56

.Lc0b_final:
	s_add_i32 s55, s52, 0xfff80080
	s_and_b64 s[10:11], s[10:11], exec
	s_cselect_b32 s60, s46, s55
	s_cselect_b32 s55, s47, s53
	s_add_i32 s10, 0, 0x10000
	v_add_u32_e32 v0, s10, v157
	v_add_u32_e32 v147, s10, v158
	s_add_i32 s10, 0, 0x14000
	ds_read_b128 v[164:167], v0
	ds_read_b128 v[168:171], v0 offset:2048
	ds_read_b128 v[172:175], v147
	ds_read_b128 v[176:179], v147 offset:2048
	v_add_u32_e32 v0, s10, v157
	v_add_u32_e32 v147, s10, v158
	ds_read_b128 v[180:183], v0
	ds_read_b128 v[184:187], v0 offset:2048
	ds_read_b128 v[188:191], v147
	ds_read_b128 v[192:195], v147 offset:2048
	s_or_b32 s56, s60, 0x80
	s_or_b32 s58, s55, 0x80
	s_mov_b32 m0, s37
	ds_read_b128 v[196:199], v161
	ds_read_b128 v[204:207], v161 offset:2048
	ds_read_b128 v[208:211], v162
	ds_read_b128 v[212:215], v162 offset:2048
	ds_read_b128 v[216:219], v161 offset:4096
	ds_read_b128 v[220:223], v161 offset:6144
	ds_read_b128 v[224:227], v162 offset:4096
	ds_read_b128 v[228:231], v162 offset:6144
	buffer_load_dwordx4 v151, s[48:51], s52 offen lds
	s_mov_b32 m0, s38
	s_nop 0
	buffer_load_dwordx4 v155, s[48:51], s52 offen lds
	s_waitcnt vmcnt(16)
	s_waitcnt lgkmcnt(0)
	s_barrier
	s_waitcnt lgkmcnt(0)
	v_readlane_b32 s32, v255, 9
	s_cmp_lg_u32 s32, 0
	s_cbranch_scc1 .Lei_p1_c0b
	s_cmp_lt_i32 s63, 1
	s_cbranch_scc1 .Lei_p1_c0b
	v_readlane_b32 s32, v255, 12
	s_nop 1
	v_mov_b32_e32 v232, s32
	v_readlane_b32 s32, v255, 13
	s_nop 1
	v_mov_b32_e32 v233, s32
	s_mul_i32 s32, s63, 0x220
	s_sub_u32 s32, s32, 32
	v_mov_b32_e32 v234, s32
	v_mov_b32_e32 v235, 0
	v_lshl_add_u64 v[232:233], v[232:233], 0, v[234:235]
	v_readlane_b32 s32, v255, 17
	s_nop 1
	v_mov_b32_e32 v235, s32
	global_load_dword v234, v[232:233], off sc1
	ds_read_b32 v235, v235
.Lei_p1_c0b:
	v_mfma_f32_16x16x32_f16 v[94:97], v[164:167], v[196:199], v[94:97]
	v_mfma_f32_16x16x32_f16 v[98:101], v[168:171], v[196:199], v[98:101]
	v_mfma_f32_16x16x32_f16 v[62:65], v[164:167], v[204:207], v[62:65]
	v_mfma_f32_16x16x32_f16 v[74:77], v[168:171], v[204:207], v[74:77]
	v_mfma_f32_16x16x32_f16 v[34:37], v[164:167], v[216:219], v[34:37]
	v_mfma_f32_16x16x32_f16 v[42:45], v[168:171], v[216:219], v[42:45]
	v_mfma_f32_16x16x32_f16 v[14:17], v[164:167], v[220:223], v[14:17]
	v_mfma_f32_16x16x32_f16 v[22:25], v[168:171], v[220:223], v[22:25]
	v_mfma_f32_16x16x32_f16 v[94:97], v[172:175], v[208:211], v[94:97]
	v_mfma_f32_16x16x32_f16 v[98:101], v[176:179], v[208:211], v[98:101]
	v_mfma_f32_16x16x32_f16 v[62:65], v[172:175], v[212:215], v[62:65]
	v_mfma_f32_16x16x32_f16 v[74:77], v[176:179], v[212:215], v[74:77]
	v_mfma_f32_16x16x32_f16 v[34:37], v[172:175], v[224:227], v[34:37]
	v_mfma_f32_16x16x32_f16 v[42:45], v[176:179], v[224:227], v[42:45]
	v_mfma_f32_16x16x32_f16 v[14:17], v[172:175], v[228:231], v[14:17]
	v_mfma_f32_16x16x32_f16 v[22:25], v[176:179], v[228:231], v[22:25]
	v_mfma_f32_16x16x32_f16 v[122:125], v[180:183], v[196:199], v[122:125]
	v_mfma_f32_16x16x32_f16 v[126:129], v[184:187], v[196:199], v[126:129]
	v_mfma_f32_16x16x32_f16 v[110:113], v[180:183], v[204:207], v[110:113]
	v_mfma_f32_16x16x32_f16 v[118:121], v[184:187], v[204:207], v[118:121]
	v_mfma_f32_16x16x32_f16 v[86:89], v[180:183], v[216:219], v[86:89]
	v_mfma_f32_16x16x32_f16 v[102:105], v[184:187], v[216:219], v[102:105]
	v_mfma_f32_16x16x32_f16 v[70:73], v[180:183], v[220:223], v[70:73]
	v_mfma_f32_16x16x32_f16 v[78:81], v[184:187], v[220:223], v[78:81]
	v_mfma_f32_16x16x32_f16 v[122:125], v[188:191], v[208:211], v[122:125]
	v_mfma_f32_16x16x32_f16 v[126:129], v[192:195], v[208:211], v[126:129]
	v_mfma_f32_16x16x32_f16 v[110:113], v[188:191], v[212:215], v[110:113]
	v_mfma_f32_16x16x32_f16 v[118:121], v[192:195], v[212:215], v[118:121]
	v_mfma_f32_16x16x32_f16 v[86:89], v[188:191], v[224:227], v[86:89]
	v_mfma_f32_16x16x32_f16 v[102:105], v[192:195], v[224:227], v[102:105]
	v_mfma_f32_16x16x32_f16 v[70:73], v[188:191], v[228:231], v[70:73]
	v_mfma_f32_16x16x32_f16 v[78:81], v[192:195], v[228:231], v[78:81]
	s_barrier
	s_mov_b32 s10, s50
	s_mov_b32 s11, s51
	ds_read_b128 v[196:199], v161 offset:16384
	ds_read_b128 v[204:207], v161 offset:18432
	ds_read_b128 v[208:211], v162 offset:16384
	ds_read_b128 v[212:215], v162 offset:18432
	ds_read_b128 v[216:219], v161 offset:20480
	ds_read_b128 v[220:223], v161 offset:22528
	ds_read_b128 v[224:227], v162 offset:20480
	ds_read_b128 v[228:231], v162 offset:22528
	s_add_i32 s61, s55, 0x80000
	s_waitcnt vmcnt(10)
	s_waitcnt lgkmcnt(0)
	s_barrier
	s_waitcnt lgkmcnt(0)
	v_mfma_f32_16x16x32_f16 v[54:57], v[164:167], v[196:199], v[54:57]
	v_mfma_f32_16x16x32_f16 v[66:69], v[168:171], v[196:199], v[66:69]
	v_mfma_f32_16x16x32_f16 v[30:33], v[164:167], v[204:207], v[30:33]
	v_mfma_f32_16x16x32_f16 v[38:41], v[168:171], v[204:207], v[38:41]
	v_mfma_f32_16x16x32_f16 v[10:13], v[164:167], v[216:219], v[10:13]
	v_mfma_f32_16x16x32_f16 v[18:21], v[168:171], v[216:219], v[18:21]
	v_mfma_f32_16x16x32_f16 v[2:5], v[164:167], v[220:223], v[2:5]
	v_mfma_f32_16x16x32_f16 v[6:9], v[168:171], v[220:223], v[6:9]
	v_mfma_f32_16x16x32_f16 v[54:57], v[172:175], v[208:211], v[54:57]
	v_mfma_f32_16x16x32_f16 v[66:69], v[176:179], v[208:211], v[66:69]
	v_mfma_f32_16x16x32_f16 v[30:33], v[172:175], v[212:215], v[30:33]
	v_mfma_f32_16x16x32_f16 v[38:41], v[176:179], v[212:215], v[38:41]
	v_mfma_f32_16x16x32_f16 v[10:13], v[172:175], v[224:227], v[10:13]
	v_mfma_f32_16x16x32_f16 v[18:21], v[176:179], v[224:227], v[18:21]
	v_mfma_f32_16x16x32_f16 v[2:5], v[172:175], v[228:231], v[2:5]
	v_mfma_f32_16x16x32_f16 v[6:9], v[176:179], v[228:231], v[6:9]
	v_mfma_f32_16x16x32_f16 v[106:109], v[180:183], v[196:199], v[106:109]
	v_mfma_f32_16x16x32_f16 v[114:117], v[184:187], v[196:199], v[114:117]
	v_mfma_f32_16x16x32_f16 v[82:85], v[180:183], v[204:207], v[82:85]
	v_mfma_f32_16x16x32_f16 v[90:93], v[184:187], v[204:207], v[90:93]
	v_mfma_f32_16x16x32_f16 v[46:49], v[180:183], v[216:219], v[46:49]
	v_mfma_f32_16x16x32_f16 v[58:61], v[184:187], v[216:219], v[58:61]
	v_mfma_f32_16x16x32_f16 v[26:29], v[180:183], v[220:223], v[26:29]
	v_mfma_f32_16x16x32_f16 v[50:53], v[184:187], v[220:223], v[50:53]
	v_mfma_f32_16x16x32_f16 v[106:109], v[188:191], v[208:211], v[106:109]
	v_mfma_f32_16x16x32_f16 v[114:117], v[192:195], v[208:211], v[114:117]
	v_mfma_f32_16x16x32_f16 v[82:85], v[188:191], v[212:215], v[82:85]
	v_mfma_f32_16x16x32_f16 v[90:93], v[192:195], v[212:215], v[90:93]
	v_mfma_f32_16x16x32_f16 v[46:49], v[188:191], v[224:227], v[46:49]
	v_mfma_f32_16x16x32_f16 v[58:61], v[192:195], v[224:227], v[58:61]
	v_mfma_f32_16x16x32_f16 v[26:29], v[188:191], v[228:231], v[26:29]
	v_mfma_f32_16x16x32_f16 v[50:53], v[192:195], v[228:231], v[50:53]
	s_barrier
	s_add_i32 s61, 0, 0x18000
	v_add_u32_e32 v0, s61, v157
	v_add_u32_e32 v147, s61, v158
	s_add_i32 s61, 0, 0x1c000
	ds_read_b128 v[164:167], v0
	ds_read_b128 v[168:171], v0 offset:2048
	ds_read_b128 v[172:175], v147
	ds_read_b128 v[176:179], v147 offset:2048
	v_add_u32_e32 v0, s61, v157
	v_add_u32_e32 v147, s61, v158
	ds_read_b128 v[180:183], v0
	ds_read_b128 v[184:187], v0 offset:2048
	ds_read_b128 v[188:191], v147
	ds_read_b128 v[192:195], v147 offset:2048
	s_add_i32 s60, s60, 0x80000
	ds_read_b128 v[196:199], v161 offset:32768
	ds_read_b128 v[204:207], v161 offset:34816
	ds_read_b128 v[208:211], v162 offset:32768
	ds_read_b128 v[212:215], v162 offset:34816
	ds_read_b128 v[216:219], v161 offset:36864
	ds_read_b128 v[220:223], v161 offset:38912
	ds_read_b128 v[224:227], v162 offset:36864
	ds_read_b128 v[228:231], v162 offset:38912
	s_waitcnt vmcnt(0)
	s_waitcnt lgkmcnt(0)
	s_barrier
	s_waitcnt lgkmcnt(0)
	v_mfma_f32_16x16x32_f16 v[94:97], v[164:167], v[196:199], v[94:97]
	v_mfma_f32_16x16x32_f16 v[98:101], v[168:171], v[196:199], v[98:101]
	v_mfma_f32_16x16x32_f16 v[62:65], v[164:167], v[204:207], v[62:65]
	v_mfma_f32_16x16x32_f16 v[74:77], v[168:171], v[204:207], v[74:77]
	v_mfma_f32_16x16x32_f16 v[34:37], v[164:167], v[216:219], v[34:37]
	v_mfma_f32_16x16x32_f16 v[42:45], v[168:171], v[216:219], v[42:45]
	v_mfma_f32_16x16x32_f16 v[14:17], v[164:167], v[220:223], v[14:17]
	v_mfma_f32_16x16x32_f16 v[22:25], v[168:171], v[220:223], v[22:25]
	v_mfma_f32_16x16x32_f16 v[94:97], v[172:175], v[208:211], v[94:97]
	v_mfma_f32_16x16x32_f16 v[98:101], v[176:179], v[208:211], v[98:101]
	v_mfma_f32_16x16x32_f16 v[62:65], v[172:175], v[212:215], v[62:65]
	v_mfma_f32_16x16x32_f16 v[74:77], v[176:179], v[212:215], v[74:77]
	v_mfma_f32_16x16x32_f16 v[34:37], v[172:175], v[224:227], v[34:37]
	v_mfma_f32_16x16x32_f16 v[42:45], v[176:179], v[224:227], v[42:45]
	v_mfma_f32_16x16x32_f16 v[14:17], v[172:175], v[228:231], v[14:17]
	v_mfma_f32_16x16x32_f16 v[22:25], v[176:179], v[228:231], v[22:25]
	v_mfma_f32_16x16x32_f16 v[122:125], v[180:183], v[196:199], v[122:125]
	v_mfma_f32_16x16x32_f16 v[126:129], v[184:187], v[196:199], v[126:129]
	v_mfma_f32_16x16x32_f16 v[110:113], v[180:183], v[204:207], v[110:113]
	v_mfma_f32_16x16x32_f16 v[118:121], v[184:187], v[204:207], v[118:121]
	v_mfma_f32_16x16x32_f16 v[86:89], v[180:183], v[216:219], v[86:89]
	v_mfma_f32_16x16x32_f16 v[102:105], v[184:187], v[216:219], v[102:105]
	v_mfma_f32_16x16x32_f16 v[70:73], v[180:183], v[220:223], v[70:73]
	v_mfma_f32_16x16x32_f16 v[78:81], v[184:187], v[220:223], v[78:81]
	v_mfma_f32_16x16x32_f16 v[122:125], v[188:191], v[208:211], v[122:125]
	v_mfma_f32_16x16x32_f16 v[126:129], v[192:195], v[208:211], v[126:129]
	v_mfma_f32_16x16x32_f16 v[110:113], v[188:191], v[212:215], v[110:113]
	v_mfma_f32_16x16x32_f16 v[118:121], v[192:195], v[212:215], v[118:121]
	v_mfma_f32_16x16x32_f16 v[86:89], v[188:191], v[224:227], v[86:89]
	v_mfma_f32_16x16x32_f16 v[102:105], v[192:195], v[224:227], v[102:105]
	v_mfma_f32_16x16x32_f16 v[70:73], v[188:191], v[228:231], v[70:73]
	v_mfma_f32_16x16x32_f16 v[78:81], v[192:195], v[228:231], v[78:81]
	s_barrier
	ds_read_b128 v[196:199], v161 offset:49152
	ds_read_b128 v[204:207], v161 offset:51200
	ds_read_b128 v[208:211], v162 offset:49152
	ds_read_b128 v[212:215], v162 offset:51200
	ds_read_b128 v[216:219], v161 offset:53248
	ds_read_b128 v[220:223], v161 offset:55296
	ds_read_b128 v[224:227], v162 offset:53248
	ds_read_b128 v[228:231], v162 offset:55296
	s_add_i32 s55, s55, 0x80080
	s_waitcnt vmcnt(0)
	s_waitcnt lgkmcnt(0)
	s_barrier
	s_waitcnt lgkmcnt(0)
	v_readlane_b32 s32, v255, 9
	s_cmp_lg_u32 s32, 0
	s_cbranch_scc1 .Lei_p2_c0b
	s_cmp_lt_i32 s63, 1
	s_cbranch_scc1 .Lei_p2_c0b
	v_sub_u32_e32 v234, v234, v235
	s_nop 0
	v_readfirstlane_b32 s32, v234
	s_cmp_lt_i32 s32, 0
	s_cbranch_scc1 .Lei_p2_c0b
	buffer_inv sc1
	v_writelane_b32 v255, 1, 56

.LBB0_340:
	s_mov_b32 s26, s63
	v_readlane_b32 s32, v255, 0
	s_sub_i32 s32, s32, s59
	v_mov_b32_e32 v232, s32
	v_readlane_b32 s32, v255, 16
	v_ashrrev_i32_e32 v233, 31, v232
	s_nop 0
	v_and_b32_e32 v233, s32, v233
	v_add_u32_e32 v232, v232, v233
	s_nop 0
	v_readfirstlane_b32 s32, v232
	s_cmpk_gt_i32 s32, 0x7f
	s_cbranch_scc0 .Lbyp_no
	s_xor_b64 s[12:13], s[8:9], -1
	v_writelane_b32 v255, 0, 56
	s_branch .LBB0_407

.Lc0r_final:
	s_add_i32 s81, s64, 0x80
	s_and_b64 s[10:11], s[10:11], exec
	s_cselect_b32 s84, s24, s81
	s_cselect_b32 s85, s25, s65
	s_add_i32 s10, 0, 0x10000
	v_add_u32_e32 v3, s10, v208
	v_add_u32_e32 v144, s10, v209
	s_add_i32 s10, 0, 0x14000
	ds_read_b128 v[116:119], v3
	ds_read_b128 v[120:123], v3 offset:2048
	ds_read_b128 v[140:143], v144
	ds_read_b128 v[144:147], v144 offset:2048
	v_add_u32_e32 v3, s10, v208
	v_add_u32_e32 v176, s10, v209
	ds_read_b128 v[164:167], v3
	ds_read_b128 v[168:171], v3 offset:2048
	ds_read_b128 v[172:175], v176
	ds_read_b128 v[176:179], v176 offset:2048
	s_add_i32 s81, s84, 0x80
	s_add_i32 s82, s85, 0x80
	s_add_i32 s10, s29, s64
	s_mov_b32 m0, s53
	ds_read_b128 v[180:183], v214
	ds_read_b128 v[184:187], v214 offset:2048
	ds_read_b128 v[188:191], v215
	ds_read_b128 v[192:195], v215 offset:2048
	ds_read_b128 v[196:199], v214 offset:4096
	ds_read_b128 v[216:219], v214 offset:6144
	ds_read_b128 v[220:223], v215 offset:4096
	ds_read_b128 v[224:227], v215 offset:6144
	buffer_load_dwordx4 v204, s[48:51], s10 offen lds
	s_mov_b32 m0, s54
	s_nop 0
	buffer_load_dwordx4 v206, s[48:51], s10 offen lds
	s_waitcnt vmcnt(12)
	s_waitcnt lgkmcnt(0)
	s_barrier
	s_waitcnt lgkmcnt(0)
	v_readlane_b32 s32, v255, 9
	s_cmp_lg_u32 s32, 0
	s_cbranch_scc1 .Lei_p1_c0r
	s_cmp_lt_i32 s26, 1
	s_cbranch_scc1 .Lei_p1_c0r
	v_readlane_b32 s32, v255, 12
	s_nop 1
	v_mov_b32_e32 v232, s32
	v_readlane_b32 s32, v255, 13
	s_nop 1
	v_mov_b32_e32 v233, s32
	s_mul_i32 s32, s26, 0x220
	s_sub_u32 s32, s32, 32
	v_mov_b32_e32 v234, s32
	v_mov_b32_e32 v235, 0
	v_lshl_add_u64 v[232:233], v[232:233], 0, v[234:235]
	v_readlane_b32 s32, v255, 17
	s_nop 1
	v_mov_b32_e32 v235, s32
	global_load_dword v234, v[232:233], off sc1
	ds_read_b32 v235, v235
.Lei_p1_c0r:
	v_mfma_f32_16x16x32_bf16 v[160:163], v[116:119], v[180:183], v[160:163]
	v_mfma_f32_16x16x32_bf16 v[152:155], v[120:123], v[180:183], v[152:155]
	v_mfma_f32_16x16x32_bf16 v[132:135], v[116:119], v[184:187], v[132:135]
	v_mfma_f32_16x16x32_bf16 v[124:127], v[120:123], v[184:187], v[124:127]
	v_mfma_f32_16x16x32_bf16 v[108:111], v[116:119], v[196:199], v[108:111]
	v_mfma_f32_16x16x32_bf16 v[100:103], v[120:123], v[196:199], v[100:103]
	v_mfma_f32_16x16x32_bf16 v[92:95], v[116:119], v[216:219], v[92:95]
	v_mfma_f32_16x16x32_bf16 v[84:87], v[120:123], v[216:219], v[84:87]
	v_mfma_f32_16x16x32_bf16 v[160:163], v[140:143], v[188:191], v[160:163]
	v_mfma_f32_16x16x32_bf16 v[152:155], v[144:147], v[188:191], v[152:155]
	v_mfma_f32_16x16x32_bf16 v[132:135], v[140:143], v[192:195], v[132:135]
	v_mfma_f32_16x16x32_bf16 v[124:127], v[144:147], v[192:195], v[124:127]
	v_mfma_f32_16x16x32_bf16 v[108:111], v[140:143], v[220:223], v[108:111]
	v_mfma_f32_16x16x32_bf16 v[100:103], v[144:147], v[220:223], v[100:103]
	v_mfma_f32_16x16x32_bf16 v[92:95], v[140:143], v[224:227], v[92:95]
	v_mfma_f32_16x16x32_bf16 v[84:87], v[144:147], v[224:227], v[84:87]
	v_mfma_f32_16x16x32_bf16 v[156:159], v[164:167], v[180:183], v[156:159]
	v_mfma_f32_16x16x32_bf16 v[148:151], v[168:171], v[180:183], v[148:151]
	v_mfma_f32_16x16x32_bf16 v[136:139], v[164:167], v[184:187], v[136:139]
	v_mfma_f32_16x16x32_bf16 v[128:131], v[168:171], v[184:187], v[128:131]
	v_mfma_f32_16x16x32_bf16 v[112:115], v[164:167], v[196:199], v[112:115]
	v_mfma_f32_16x16x32_bf16 v[104:107], v[168:171], v[196:199], v[104:107]
	v_mfma_f32_16x16x32_bf16 v[96:99], v[164:167], v[216:219], v[96:99]
	v_mfma_f32_16x16x32_bf16 v[88:91], v[168:171], v[216:219], v[88:91]
	v_mfma_f32_16x16x32_bf16 v[156:159], v[172:175], v[188:191], v[156:159]
	v_mfma_f32_16x16x32_bf16 v[148:151], v[176:179], v[188:191], v[148:151]
	v_mfma_f32_16x16x32_bf16 v[136:139], v[172:175], v[192:195], v[136:139]
	v_mfma_f32_16x16x32_bf16 v[128:131], v[176:179], v[192:195], v[128:131]
	v_mfma_f32_16x16x32_bf16 v[112:115], v[172:175], v[220:223], v[112:115]
	v_mfma_f32_16x16x32_bf16 v[104:107], v[176:179], v[220:223], v[104:107]
	v_mfma_f32_16x16x32_bf16 v[96:99], v[172:175], v[224:227], v[96:99]
	v_mfma_f32_16x16x32_bf16 v[88:91], v[176:179], v[224:227], v[88:91]
	s_barrier
	s_mov_b32 s10, s50
	s_mov_b32 s11, s51
	ds_read_b128 v[180:183], v214 offset:16384
	ds_read_b128 v[184:187], v214 offset:18432
	ds_read_b128 v[188:191], v215 offset:16384
	ds_read_b128 v[192:195], v215 offset:18432
	ds_read_b128 v[196:199], v214 offset:20480
	ds_read_b128 v[216:219], v214 offset:22528
	ds_read_b128 v[220:223], v215 offset:20480
	ds_read_b128 v[224:227], v215 offset:22528
	s_add_i32 s85, s85, s29
	s_waitcnt vmcnt(6)
	s_waitcnt lgkmcnt(0)
	s_barrier
	s_waitcnt lgkmcnt(0)
	v_mfma_f32_16x16x32_bf16 v[76:79], v[116:119], v[180:183], v[76:79]
	v_mfma_f32_16x16x32_bf16 v[68:71], v[120:123], v[180:183], v[68:71]
	v_mfma_f32_16x16x32_bf16 v[60:63], v[116:119], v[184:187], v[60:63]
	v_mfma_f32_16x16x32_bf16 v[52:55], v[120:123], v[184:187], v[52:55]
	v_mfma_f32_16x16x32_bf16 v[44:47], v[116:119], v[196:199], v[44:47]
	v_mfma_f32_16x16x32_bf16 v[36:39], v[120:123], v[196:199], v[36:39]
	v_mfma_f32_16x16x32_bf16 v[24:27], v[116:119], v[216:219], v[24:27]
	v_mfma_f32_16x16x32_bf16 v[20:23], v[120:123], v[216:219], v[20:23]
	v_mfma_f32_16x16x32_bf16 v[76:79], v[140:143], v[188:191], v[76:79]
	v_mfma_f32_16x16x32_bf16 v[68:71], v[144:147], v[188:191], v[68:71]
	v_mfma_f32_16x16x32_bf16 v[60:63], v[140:143], v[192:195], v[60:63]
	v_mfma_f32_16x16x32_bf16 v[52:55], v[144:147], v[192:195], v[52:55]
	v_mfma_f32_16x16x32_bf16 v[44:47], v[140:143], v[220:223], v[44:47]
	v_mfma_f32_16x16x32_bf16 v[36:39], v[144:147], v[220:223], v[36:39]
	v_mfma_f32_16x16x32_bf16 v[24:27], v[140:143], v[224:227], v[24:27]
	v_mfma_f32_16x16x32_bf16 v[20:23], v[144:147], v[224:227], v[20:23]
	v_mfma_f32_16x16x32_bf16 v[80:83], v[164:167], v[180:183], v[80:83]
	v_mfma_f32_16x16x32_bf16 v[72:75], v[168:171], v[180:183], v[72:75]
	v_mfma_f32_16x16x32_bf16 v[64:67], v[164:167], v[184:187], v[64:67]
	v_mfma_f32_16x16x32_bf16 v[56:59], v[168:171], v[184:187], v[56:59]
	v_mfma_f32_16x16x32_bf16 v[48:51], v[164:167], v[196:199], v[48:51]
	v_mfma_f32_16x16x32_bf16 v[40:43], v[168:171], v[196:199], v[40:43]
	v_mfma_f32_16x16x32_bf16 v[28:31], v[164:167], v[216:219], v[28:31]
	v_mfma_f32_16x16x32_bf16 v[32:35], v[168:171], v[216:219], v[32:35]
	v_mfma_f32_16x16x32_bf16 v[80:83], v[172:175], v[188:191], v[80:83]
	v_mfma_f32_16x16x32_bf16 v[72:75], v[176:179], v[188:191], v[72:75]
	v_mfma_f32_16x16x32_bf16 v[64:67], v[172:175], v[192:195], v[64:67]
	v_mfma_f32_16x16x32_bf16 v[56:59], v[176:179], v[192:195], v[56:59]
	v_mfma_f32_16x16x32_bf16 v[48:51], v[172:175], v[220:223], v[48:51]
	v_mfma_f32_16x16x32_bf16 v[40:43], v[176:179], v[220:223], v[40:43]
	v_mfma_f32_16x16x32_bf16 v[28:31], v[172:175], v[224:227], v[28:31]
	v_mfma_f32_16x16x32_bf16 v[32:35], v[176:179], v[224:227], v[32:35]
	s_barrier
	s_add_i32 s85, 0, 0x18000
	v_add_u32_e32 v3, s85, v208
	v_add_u32_e32 v144, s85, v209
	s_add_i32 s85, 0, 0x1c000
	ds_read_b128 v[116:119], v3
	ds_read_b128 v[120:123], v3 offset:2048
	ds_read_b128 v[140:143], v144
	ds_read_b128 v[144:147], v144 offset:2048
	v_add_u32_e32 v3, s85, v208
	v_add_u32_e32 v176, s85, v209
	ds_read_b128 v[164:167], v3
	ds_read_b128 v[168:171], v3 offset:2048
	ds_read_b128 v[172:175], v176
	ds_read_b128 v[176:179], v176 offset:2048
	s_add_i32 s84, s84, s29
	ds_read_b128 v[180:183], v214 offset:32768
	ds_read_b128 v[184:187], v214 offset:34816
	ds_read_b128 v[188:191], v215 offset:32768
	ds_read_b128 v[192:195], v215 offset:34816
	ds_read_b128 v[196:199], v214 offset:36864
	ds_read_b128 v[216:219], v214 offset:38912
	ds_read_b128 v[220:223], v215 offset:36864
	ds_read_b128 v[224:227], v215 offset:38912
	s_waitcnt vmcnt(0)
	s_waitcnt lgkmcnt(0)
	s_barrier
	s_waitcnt lgkmcnt(0)
	v_mfma_f32_16x16x32_bf16 v[160:163], v[116:119], v[180:183], v[160:163]
	v_mfma_f32_16x16x32_bf16 v[152:155], v[120:123], v[180:183], v[152:155]
	v_mfma_f32_16x16x32_bf16 v[132:135], v[116:119], v[184:187], v[132:135]
	v_mfma_f32_16x16x32_bf16 v[124:127], v[120:123], v[184:187], v[124:127]
	v_mfma_f32_16x16x32_bf16 v[108:111], v[116:119], v[196:199], v[108:111]
	v_mfma_f32_16x16x32_bf16 v[100:103], v[120:123], v[196:199], v[100:103]
	v_mfma_f32_16x16x32_bf16 v[92:95], v[116:119], v[216:219], v[92:95]
	v_mfma_f32_16x16x32_bf16 v[84:87], v[120:123], v[216:219], v[84:87]
	v_mfma_f32_16x16x32_bf16 v[160:163], v[140:143], v[188:191], v[160:163]
	v_mfma_f32_16x16x32_bf16 v[152:155], v[144:147], v[188:191], v[152:155]
	v_mfma_f32_16x16x32_bf16 v[132:135], v[140:143], v[192:195], v[132:135]
	v_mfma_f32_16x16x32_bf16 v[124:127], v[144:147], v[192:195], v[124:127]
	v_mfma_f32_16x16x32_bf16 v[108:111], v[140:143], v[220:223], v[108:111]
	v_mfma_f32_16x16x32_bf16 v[100:103], v[144:147], v[220:223], v[100:103]
	v_mfma_f32_16x16x32_bf16 v[92:95], v[140:143], v[224:227], v[92:95]
	v_mfma_f32_16x16x32_bf16 v[84:87], v[144:147], v[224:227], v[84:87]
	v_mfma_f32_16x16x32_bf16 v[156:159], v[164:167], v[180:183], v[156:159]
	v_mfma_f32_16x16x32_bf16 v[148:151], v[168:171], v[180:183], v[148:151]
	v_mfma_f32_16x16x32_bf16 v[136:139], v[164:167], v[184:187], v[136:139]
	v_mfma_f32_16x16x32_bf16 v[128:131], v[168:171], v[184:187], v[128:131]
	v_mfma_f32_16x16x32_bf16 v[112:115], v[164:167], v[196:199], v[112:115]
	v_mfma_f32_16x16x32_bf16 v[104:107], v[168:171], v[196:199], v[104:107]
	v_mfma_f32_16x16x32_bf16 v[96:99], v[164:167], v[216:219], v[96:99]
	v_mfma_f32_16x16x32_bf16 v[88:91], v[168:171], v[216:219], v[88:91]
	v_mfma_f32_16x16x32_bf16 v[156:159], v[172:175], v[188:191], v[156:159]
	v_mfma_f32_16x16x32_bf16 v[148:151], v[176:179], v[188:191], v[148:151]
	v_mfma_f32_16x16x32_bf16 v[136:139], v[172:175], v[192:195], v[136:139]
	v_mfma_f32_16x16x32_bf16 v[128:131], v[176:179], v[192:195], v[128:131]
	v_mfma_f32_16x16x32_bf16 v[112:115], v[172:175], v[220:223], v[112:115]
	v_mfma_f32_16x16x32_bf16 v[104:107], v[176:179], v[220:223], v[104:107]
	v_mfma_f32_16x16x32_bf16 v[96:99], v[172:175], v[224:227], v[96:99]
	v_mfma_f32_16x16x32_bf16 v[88:91], v[176:179], v[224:227], v[88:91]
	s_barrier
	ds_read_b128 v[180:183], v214 offset:49152
	ds_read_b128 v[184:187], v214 offset:51200
	ds_read_b128 v[188:191], v215 offset:49152
	ds_read_b128 v[192:195], v215 offset:51200
	ds_read_b128 v[196:199], v214 offset:53248
	ds_read_b128 v[216:219], v214 offset:55296
	ds_read_b128 v[220:223], v215 offset:53248
	ds_read_b128 v[224:227], v215 offset:55296
	s_add_i32 s82, s82, s29
	s_waitcnt vmcnt(0)
	s_waitcnt lgkmcnt(0)
	s_barrier
	s_waitcnt lgkmcnt(0)
	v_readlane_b32 s32, v255, 9
	s_cmp_lg_u32 s32, 0
	s_cbranch_scc1 .Lei_p2_c0r
	s_cmp_lt_i32 s26, 1
	s_cbranch_scc1 .Lei_p2_c0r
	v_sub_u32_e32 v234, v234, v235
	s_nop 0
	v_readfirstlane_b32 s32, v234
	s_cmp_lt_i32 s32, 0
	s_cbranch_scc1 .Lei_p2_c0r
	buffer_inv sc1
	v_writelane_b32 v255, 1, 56
